# GEMM K-loops: LDS-DMA issue balanced over the four phases (4,4,4,4 pieces per wave instead of 2,6,2,6; q0 pieces moved to phase 3, q2 pieces to the next phase 1), waits vmcnt(8,6,8,6)
# speedup vs baseline: 1.0020x; 1.0012x over previous
.LBB0_131:
	s_mov_b32 s0, s19
	s_mov_b32 s1, s99
	s_mov_b64 s[6:7], s[40:41]
	v_writelane_b32 v255, s0, 6
	v_mbcnt_lo_u32_b32 v0, -1, 0
	v_mbcnt_hi_u32_b32 v0, -1, v0
	s_nop 0
	v_add_u32_e32 v0, s69, v0
	v_writelane_b32 v255, s1, 7
	v_readlane_b32 s0, v252, 22
	v_readlane_b32 s1, v252, 23
	s_andn2_b64 vcc, exec, s[0:1]
	v_readfirstlane_b32 s0, v0
	s_cbranch_vccnz .LBB0_163
	v_lshlrev_b32_e32 v2, 4, v0
	v_add_u32_e32 v3, 0x2000, v2
	v_ashrrev_i32_e32 v4, 31, v3
	v_lshrrev_b32_e32 v4, 22, v4
	v_add_u32_e32 v4, v3, v4
	v_ashrrev_i32_e32 v10, 10, v4
	v_mul_i32_i24_e32 v4, 0x400, v10
	v_sub_u32_e32 v3, v3, v4
	v_lshrrev_b32_e32 v4, 4, v3
	v_bitop3_b32 v3, v4, v3, 32 bitop3:0x6c
	v_ashrrev_i32_e32 v4, 31, v3
	s_add_u32 s16, s6, 0x13400000
	v_readlane_b32 s4, v255, 6
	v_lshrrev_b32_e32 v4, 26, v4
	s_addc_u32 s17, s7, 0
	s_mul_hi_u32 s1, s4, 0x1c00000
	s_mul_i32 s4, s4, 0x1c00000
	v_add_u32_e32 v4, v3, v4
	v_lshlrev_b32_e32 v5, 3, v10
	s_add_u32 s4, s6, s4
	v_ashrrev_i32_e32 v11, 6, v4
	v_and_b32_e32 v5, -16, v5
	s_addc_u32 s1, s7, s1
	v_add_u32_e32 v5, v11, v5
	s_add_u32 s19, s4, 0x100000
	v_and_b32_e32 v6, 3, v11
	s_mov_b32 s4, 0xfffe0
	v_lshrrev_b32_e32 v7, 2, v5
	v_lshlrev_b32_e32 v8, 1, v5
	v_and_b32_e32 v4, 0xc0, v4
	v_and_or_b32 v6, v5, s4, v6
	v_and_b32_e32 v7, 4, v7
	v_and_b32_e32 v8, 24, v8
	v_sub_u32_e32 v3, v3, v4
	v_or3_b32 v6, v6, v7, v8
	v_lshlrev_b32_e32 v7, 5, v10
	v_ashrrev_i16_sdwa v3, v206, sext(v3) dst_sel:DWORD dst_unused:UNUSED_PAD src0_sel:DWORD src1_sel:BYTE_0
	v_and_b32_e32 v7, 32, v7
	v_bfe_i32 v12, v3, 0, 16
	v_add_lshl_u32 v3, v7, v12, 1
	v_lshl_add_u32 v134, v6, 12, v3
	v_lshl_add_u32 v136, v5, 12, v3
	v_bfe_i32 v3, v0, 27, 1
	v_lshrrev_b32_e32 v3, 22, v3
	v_add_u32_e32 v3, v2, v3
	v_and_b32_e32 v3, 0xfffffc00, v3
	v_sub_u32_e32 v2, v2, v3
	v_lshrrev_b32_e32 v3, 4, v2
	v_ashrrev_i32_e32 v4, 31, v0
	v_bitop3_b32 v2, v3, v2, 32 bitop3:0x6c
	v_lshrrev_b32_e32 v4, 26, v4
	v_ashrrev_i32_e32 v3, 31, v2
	v_add_u32_e32 v4, v0, v4
	v_lshrrev_b32_e32 v3, 26, v3
	v_ashrrev_i32_e32 v14, 6, v4
	v_add_u32_e32 v3, v2, v3
	v_lshlrev_b32_e32 v4, 3, v14
	v_ashrrev_i32_e32 v13, 6, v3
	v_and_b32_e32 v4, -16, v4
	v_add_u32_e32 v4, v13, v4
	v_and_b32_e32 v5, 3, v13
	v_lshrrev_b32_e32 v6, 2, v4
	v_lshlrev_b32_e32 v7, 1, v4
	v_and_b32_e32 v3, 0xc0, v3
	v_readlane_b32 s5, v255, 7
	s_addc_u32 s28, s1, 0
	s_ashr_i32 s14, s0, 6
	v_and_or_b32 v5, v4, s4, v5
	v_and_b32_e32 v6, 4, v6
	v_and_b32_e32 v7, 24, v7
	v_sub_u32_e32 v2, v2, v3
	s_ashr_i32 s1, s0, 8
	s_lshl_b32 s29, s14, 10
	v_or3_b32 v5, v5, v6, v7
	v_lshlrev_b32_e32 v6, 5, v14
	v_ashrrev_i16_sdwa v2, v206, sext(v2) dst_sel:DWORD dst_unused:UNUSED_PAD src0_sel:DWORD src1_sel:BYTE_0
	v_readlane_b32 s4, v254, 26
	v_and_b32_e32 v6, 32, v6
	v_bfe_i32 v15, v2, 0, 16
	v_readlane_b32 s5, v254, 27
	s_add_u32 s8, s19, s4
	v_add_lshl_u32 v2, v6, v15, 1
	s_addc_u32 s9, s28, s5
	s_add_i32 s48, s29, 0
	v_lshl_add_u32 v138, v5, 12, v2
	s_add_i32 m0, s48, 0x10000
	v_lshl_add_u32 v140, v4, 12, v2
	global_load_lds_dwordx4 v138, s[8:9]
	s_add_i32 m0, s48, 0x12000
	s_add_u32 s4, s8, 0x80000
	global_load_lds_dwordx4 v134, s[8:9]
	s_addc_u32 s5, s9, 0
	s_add_i32 m0, s48, 0x14000
	v_mov_b32_e32 v139, v1
	global_load_lds_dwordx4 v138, s[4:5]
	s_add_i32 m0, s48, 0x16000
	v_mov_b32_e32 v135, v1
	global_load_lds_dwordx4 v134, s[4:5]
	v_readlane_b32 s4, v254, 24
	v_readlane_b32 s5, v254, 25
	s_add_u32 s10, s16, s4
	s_addc_u32 s11, s17, s5
	s_add_u32 s74, s10, s44
	s_addc_u32 s75, s11, s45
	s_add_i32 s49, s48, 0x2000
	s_mov_b32 m0, s48
	s_add_u32 s4, s10, 0x80000
	global_load_lds_dwordx4 v140, s[10:11]
	s_mov_b32 m0, s49
	s_addc_u32 s5, s11, 0
	s_add_i32 s50, s48, 0x4000
	global_load_lds_dwordx4 v136, s[10:11]
	s_mov_b32 m0, s50
	s_add_i32 s51, s48, 0x6000
	global_load_lds_dwordx4 v140, s[4:5]
	s_mov_b32 m0, s51
	v_mov_b32_e32 v141, v1
	global_load_lds_dwordx4 v136, s[4:5]
	v_mov_b32_e32 v137, v1
	s_cmp_eq_u32 s1, 1
	v_lshl_add_u64 v[8:9], s[8:9], 0, v[138:139]
	v_lshl_add_u64 v[6:7], s[8:9], 0, v[134:135]
	v_lshl_add_u64 v[2:3], s[10:11], 0, v[140:141]
	s_cselect_b64 s[4:5], -1, 0
	s_cmp_lg_u32 s1, 1
	v_lshl_add_u64 v[4:5], s[10:11], 0, v[136:137]
	s_cbranch_scc1 .LBB0_134
	s_barrier

.LBB0_140:
	s_add_u32 s10, s8, 0xfff80080
	s_addc_u32 s11, s9, -1
	s_add_i32 s60, 0, 0x10000
	s_cmp_eq_u32 s59, 28
	s_cselect_b32 s15, s0, s11
	s_cselect_b32 s14, s1, s10
	v_add_u32_e32 v0, s60, v167
	s_cselect_b32 s11, s25, s58
	s_cselect_b32 s10, s27, s57
	s_add_i32 s62, 0, 0x14000
	ds_read_b128 v[130:133], v0
	ds_read_b128 v[158:161], v0 offset:1024
	ds_read_b128 v[162:165], v0 offset:2048
	ds_read_b128 v[170:173], v0 offset:3072
	v_add_u32_e32 v0, s62, v167
	ds_read_b128 v[174:177], v0
	ds_read_b128 v[178:181], v0 offset:1024
	ds_read_b128 v[182:185], v0 offset:2048
	ds_read_b128 v[186:189], v0 offset:3072
	s_mov_b32 m0, s52
	s_nop 0
	global_load_lds_dwordx4 v140, s[74:75]
	s_mov_b32 m0, s53
	s_nop 0
	global_load_lds_dwordx4 v136, s[74:75]
	s_add_i32 m0, s48, 0xc000
	ds_read_b128 v[190:193], v169
	ds_read_b128 v[194:197], v169 offset:1024
	ds_read_b128 v[198:201], v169 offset:2048
	ds_read_b128 v[216:219], v169 offset:3072
	ds_read_b128 v[220:223], v169 offset:4096
	ds_read_b128 v[224:227], v169 offset:5120
	ds_read_b128 v[228:231], v169 offset:6144
	ds_read_b128 v[232:235], v169 offset:7168
	global_load_lds_dwordx4 v156, s[8:9]
	s_add_i32 m0, s48, 0xe000
	s_nop 0
	global_load_lds_dwordx4 v146, s[8:9]
	s_waitcnt vmcnt(8)
	s_waitcnt lgkmcnt(0)
	s_barrier
	s_setprio 1
	s_waitcnt lgkmcnt(0)
	v_mfma_f32_16x16x32_bf16 v[126:129], v[130:133], v[190:193], v[126:129]
	v_mfma_f32_16x16x32_bf16 v[122:125], v[162:165], v[190:193], v[122:125]
	v_mfma_f32_16x16x32_bf16 v[110:113], v[130:133], v[198:201], v[110:113]
	v_mfma_f32_16x16x32_bf16 v[106:109], v[162:165], v[198:201], v[106:109]
	v_mfma_f32_16x16x32_bf16 v[94:97], v[130:133], v[220:223], v[94:97]
	v_mfma_f32_16x16x32_bf16 v[90:93], v[162:165], v[220:223], v[90:93]
	v_mfma_f32_16x16x32_bf16 v[78:81], v[130:133], v[228:231], v[78:81]
	v_mfma_f32_16x16x32_bf16 v[74:77], v[162:165], v[228:231], v[74:77]
	v_mfma_f32_16x16x32_bf16 v[126:129], v[158:161], v[194:197], v[126:129]
	v_mfma_f32_16x16x32_bf16 v[122:125], v[170:173], v[194:197], v[122:125]
	v_mfma_f32_16x16x32_bf16 v[110:113], v[158:161], v[216:219], v[110:113]
	v_mfma_f32_16x16x32_bf16 v[106:109], v[170:173], v[216:219], v[106:109]
	v_mfma_f32_16x16x32_bf16 v[94:97], v[158:161], v[224:227], v[94:97]
	v_mfma_f32_16x16x32_bf16 v[90:93], v[170:173], v[224:227], v[90:93]
	v_mfma_f32_16x16x32_bf16 v[78:81], v[158:161], v[232:235], v[78:81]
	v_mfma_f32_16x16x32_bf16 v[74:77], v[170:173], v[232:235], v[74:77]
	s_setprio 0
	s_setprio 1
	v_mfma_f32_16x16x32_bf16 v[118:121], v[174:177], v[190:193], v[118:121]
	v_mfma_f32_16x16x32_bf16 v[114:117], v[182:185], v[190:193], v[114:117]
	v_mfma_f32_16x16x32_bf16 v[102:105], v[174:177], v[198:201], v[102:105]
	v_mfma_f32_16x16x32_bf16 v[98:101], v[182:185], v[198:201], v[98:101]
	v_mfma_f32_16x16x32_bf16 v[86:89], v[174:177], v[220:223], v[86:89]
	v_mfma_f32_16x16x32_bf16 v[82:85], v[182:185], v[220:223], v[82:85]
	v_mfma_f32_16x16x32_bf16 v[70:73], v[174:177], v[228:231], v[70:73]
	v_mfma_f32_16x16x32_bf16 v[66:69], v[182:185], v[228:231], v[66:69]
	v_mfma_f32_16x16x32_bf16 v[118:121], v[178:181], v[194:197], v[118:121]
	v_mfma_f32_16x16x32_bf16 v[114:117], v[186:189], v[194:197], v[114:117]
	v_mfma_f32_16x16x32_bf16 v[102:105], v[178:181], v[216:219], v[102:105]
	v_mfma_f32_16x16x32_bf16 v[98:101], v[186:189], v[216:219], v[98:101]
	v_mfma_f32_16x16x32_bf16 v[86:89], v[178:181], v[224:227], v[86:89]
	v_mfma_f32_16x16x32_bf16 v[82:85], v[186:189], v[224:227], v[82:85]
	v_mfma_f32_16x16x32_bf16 v[70:73], v[178:181], v[232:235], v[70:73]
	v_mfma_f32_16x16x32_bf16 v[66:69], v[186:189], v[232:235], v[66:69]
	s_setprio 0
	s_barrier
	s_add_i32 s60, s60, s29
	s_add_u32 s72, s10, s44
	s_addc_u32 s73, s11, s45
	s_mov_b32 m0, s60
	ds_read_b128 v[190:193], v169 offset:16384
	ds_read_b128 v[194:197], v169 offset:17408
	ds_read_b128 v[198:201], v169 offset:18432
	ds_read_b128 v[216:219], v169 offset:19456
	ds_read_b128 v[220:223], v169 offset:20480
	ds_read_b128 v[224:227], v169 offset:21504
	ds_read_b128 v[228:231], v169 offset:22528
	ds_read_b128 v[232:235], v169 offset:23552
	global_load_lds_dwordx4 v138, s[10:11]
	s_add_i32 m0, s60, 0x2000
	s_add_u32 s60, s10, 0x80000
	s_addc_u32 s61, s11, 0
	s_add_i32 s62, s62, s29
	global_load_lds_dwordx4 v134, s[10:11]
	s_mov_b32 m0, s62
	s_add_u32 s74, s14, s44
	s_addc_u32 s75, s15, s45
	global_load_lds_dwordx4 v138, s[60:61]
	s_add_i32 m0, s62, 0x2000
	s_nop 0
	global_load_lds_dwordx4 v134, s[60:61]
	s_waitcnt vmcnt(6)
	s_waitcnt lgkmcnt(0)
	s_barrier
	s_setprio 1
	s_waitcnt lgkmcnt(0)
	v_mfma_f32_16x16x32_bf16 v[62:65], v[130:133], v[190:193], v[62:65]
	v_mfma_f32_16x16x32_bf16 v[58:61], v[162:165], v[190:193], v[58:61]
	v_mfma_f32_16x16x32_bf16 v[46:49], v[130:133], v[198:201], v[46:49]
	v_mfma_f32_16x16x32_bf16 v[42:45], v[162:165], v[198:201], v[42:45]
	v_mfma_f32_16x16x32_bf16 v[30:33], v[130:133], v[220:223], v[30:33]
	v_mfma_f32_16x16x32_bf16 v[26:29], v[162:165], v[220:223], v[26:29]
	v_mfma_f32_16x16x32_bf16 v[14:17], v[130:133], v[228:231], v[14:17]
	v_mfma_f32_16x16x32_bf16 v[10:13], v[162:165], v[228:231], v[10:13]
	v_mfma_f32_16x16x32_bf16 v[62:65], v[158:161], v[194:197], v[62:65]
	v_mfma_f32_16x16x32_bf16 v[58:61], v[170:173], v[194:197], v[58:61]
	v_mfma_f32_16x16x32_bf16 v[46:49], v[158:161], v[216:219], v[46:49]
	v_mfma_f32_16x16x32_bf16 v[42:45], v[170:173], v[216:219], v[42:45]
	v_mfma_f32_16x16x32_bf16 v[30:33], v[158:161], v[224:227], v[30:33]
	v_mfma_f32_16x16x32_bf16 v[26:29], v[170:173], v[224:227], v[26:29]
	v_mfma_f32_16x16x32_bf16 v[14:17], v[158:161], v[232:235], v[14:17]
	v_mfma_f32_16x16x32_bf16 v[10:13], v[170:173], v[232:235], v[10:13]
	s_setprio 0
	s_setprio 1
	v_mfma_f32_16x16x32_bf16 v[54:57], v[174:177], v[190:193], v[54:57]
	v_mfma_f32_16x16x32_bf16 v[50:53], v[182:185], v[190:193], v[50:53]
	v_mfma_f32_16x16x32_bf16 v[38:41], v[174:177], v[198:201], v[38:41]
	v_mfma_f32_16x16x32_bf16 v[34:37], v[182:185], v[198:201], v[34:37]
	v_mfma_f32_16x16x32_bf16 v[22:25], v[174:177], v[220:223], v[22:25]
	v_mfma_f32_16x16x32_bf16 v[18:21], v[182:185], v[220:223], v[18:21]
	v_mfma_f32_16x16x32_bf16 v[6:9], v[174:177], v[228:231], v[6:9]
	v_mfma_f32_16x16x32_bf16 v[2:5], v[182:185], v[228:231], v[2:5]
	v_mfma_f32_16x16x32_bf16 v[54:57], v[178:181], v[194:197], v[54:57]
	v_mfma_f32_16x16x32_bf16 v[50:53], v[186:189], v[194:197], v[50:53]
	v_mfma_f32_16x16x32_bf16 v[38:41], v[178:181], v[216:219], v[38:41]
	v_mfma_f32_16x16x32_bf16 v[34:37], v[186:189], v[216:219], v[34:37]
	v_mfma_f32_16x16x32_bf16 v[22:25], v[178:181], v[224:227], v[22:25]
	v_mfma_f32_16x16x32_bf16 v[18:21], v[186:189], v[224:227], v[18:21]
	v_mfma_f32_16x16x32_bf16 v[6:9], v[178:181], v[232:235], v[6:9]
	v_mfma_f32_16x16x32_bf16 v[2:5], v[186:189], v[232:235], v[2:5]
	s_setprio 0
	s_barrier
	s_add_i32 s60, 0, 0x18000
	v_add_u32_e32 v0, s60, v167
	s_add_i32 s61, 0, 0x1c000
	ds_read_b128 v[130:133], v0
	ds_read_b128 v[158:161], v0 offset:1024
	ds_read_b128 v[162:165], v0 offset:2048
	ds_read_b128 v[170:173], v0 offset:3072
	v_add_u32_e32 v0, s61, v167
	ds_read_b128 v[174:177], v0
	ds_read_b128 v[178:181], v0 offset:1024
	ds_read_b128 v[182:185], v0 offset:2048
	ds_read_b128 v[186:189], v0 offset:3072
	s_mov_b32 m0, s48
	s_nop 0
	global_load_lds_dwordx4 v140, s[14:15]
	s_mov_b32 m0, s49
	s_nop 0
	global_load_lds_dwordx4 v136, s[14:15]
	s_add_u32 s14, s14, 0x80000
	s_addc_u32 s15, s15, 0
	s_mov_b32 m0, s50
	ds_read_b128 v[190:193], v169 offset:32768
	ds_read_b128 v[194:197], v169 offset:33792
	ds_read_b128 v[198:201], v169 offset:34816
	ds_read_b128 v[216:219], v169 offset:35840
	ds_read_b128 v[220:223], v169 offset:36864
	ds_read_b128 v[224:227], v169 offset:37888
	ds_read_b128 v[228:231], v169 offset:38912
	ds_read_b128 v[232:235], v169 offset:39936
	global_load_lds_dwordx4 v140, s[14:15]
	s_mov_b32 m0, s51
	s_nop 0
	global_load_lds_dwordx4 v136, s[14:15]
	s_waitcnt vmcnt(8)
	s_waitcnt lgkmcnt(0)
	s_barrier
	s_setprio 1
	s_waitcnt lgkmcnt(0)
	v_mfma_f32_16x16x32_bf16 v[126:129], v[130:133], v[190:193], v[126:129]
	v_mfma_f32_16x16x32_bf16 v[122:125], v[162:165], v[190:193], v[122:125]
	v_mfma_f32_16x16x32_bf16 v[110:113], v[130:133], v[198:201], v[110:113]
	v_mfma_f32_16x16x32_bf16 v[106:109], v[162:165], v[198:201], v[106:109]
	v_mfma_f32_16x16x32_bf16 v[94:97], v[130:133], v[220:223], v[94:97]
	v_mfma_f32_16x16x32_bf16 v[90:93], v[162:165], v[220:223], v[90:93]
	v_mfma_f32_16x16x32_bf16 v[78:81], v[130:133], v[228:231], v[78:81]
	v_mfma_f32_16x16x32_bf16 v[74:77], v[162:165], v[228:231], v[74:77]
	v_mfma_f32_16x16x32_bf16 v[126:129], v[158:161], v[194:197], v[126:129]
	v_mfma_f32_16x16x32_bf16 v[122:125], v[170:173], v[194:197], v[122:125]
	v_mfma_f32_16x16x32_bf16 v[110:113], v[158:161], v[216:219], v[110:113]
	v_mfma_f32_16x16x32_bf16 v[106:109], v[170:173], v[216:219], v[106:109]
	v_mfma_f32_16x16x32_bf16 v[94:97], v[158:161], v[224:227], v[94:97]
	v_mfma_f32_16x16x32_bf16 v[90:93], v[170:173], v[224:227], v[90:93]
	v_mfma_f32_16x16x32_bf16 v[78:81], v[158:161], v[232:235], v[78:81]
	v_mfma_f32_16x16x32_bf16 v[74:77], v[170:173], v[232:235], v[74:77]
	s_setprio 0
	s_setprio 1
	v_mfma_f32_16x16x32_bf16 v[118:121], v[174:177], v[190:193], v[118:121]
	v_mfma_f32_16x16x32_bf16 v[114:117], v[182:185], v[190:193], v[114:117]
	v_mfma_f32_16x16x32_bf16 v[102:105], v[174:177], v[198:201], v[102:105]
	v_mfma_f32_16x16x32_bf16 v[98:101], v[182:185], v[198:201], v[98:101]
	v_mfma_f32_16x16x32_bf16 v[86:89], v[174:177], v[220:223], v[86:89]
	v_mfma_f32_16x16x32_bf16 v[82:85], v[182:185], v[220:223], v[82:85]
	v_mfma_f32_16x16x32_bf16 v[70:73], v[174:177], v[228:231], v[70:73]
	v_mfma_f32_16x16x32_bf16 v[66:69], v[182:185], v[228:231], v[66:69]
	v_mfma_f32_16x16x32_bf16 v[118:121], v[178:181], v[194:197], v[118:121]
	v_mfma_f32_16x16x32_bf16 v[114:117], v[186:189], v[194:197], v[114:117]
	v_mfma_f32_16x16x32_bf16 v[102:105], v[178:181], v[216:219], v[102:105]
	v_mfma_f32_16x16x32_bf16 v[98:101], v[186:189], v[216:219], v[98:101]
	v_mfma_f32_16x16x32_bf16 v[86:89], v[178:181], v[224:227], v[86:89]
	v_mfma_f32_16x16x32_bf16 v[82:85], v[186:189], v[224:227], v[82:85]
	v_mfma_f32_16x16x32_bf16 v[70:73], v[178:181], v[232:235], v[70:73]
	v_mfma_f32_16x16x32_bf16 v[66:69], v[186:189], v[232:235], v[66:69]
	s_setprio 0
	s_barrier
	s_add_i32 s14, s60, s29
	s_mov_b32 m0, s14
	ds_read_b128 v[190:193], v169 offset:49152
	ds_read_b128 v[194:197], v169 offset:50176
	ds_read_b128 v[198:201], v169 offset:51200
	ds_read_b128 v[216:219], v169 offset:52224
	ds_read_b128 v[220:223], v169 offset:53248
	ds_read_b128 v[224:227], v169 offset:54272
	ds_read_b128 v[228:231], v169 offset:55296
	ds_read_b128 v[232:235], v169 offset:56320
	global_load_lds_dwordx4 v138, s[72:73]
	s_add_i32 m0, s14, 0x2000
	s_add_u32 s10, s10, 0x80080
	s_addc_u32 s11, s11, 0
	s_add_i32 s14, s61, s29
	global_load_lds_dwordx4 v134, s[72:73]
	s_mov_b32 m0, s14
	s_nop 0
	global_load_lds_dwordx4 v138, s[10:11]
	s_add_i32 m0, s14, 0x2000
	s_nop 0
	global_load_lds_dwordx4 v134, s[10:11]
	s_waitcnt vmcnt(6)
	s_waitcnt lgkmcnt(0)
	s_barrier
	s_setprio 1
	s_waitcnt lgkmcnt(0)
	v_mfma_f32_16x16x32_bf16 v[62:65], v[130:133], v[190:193], v[62:65]
	v_mfma_f32_16x16x32_bf16 v[58:61], v[162:165], v[190:193], v[58:61]
	v_mfma_f32_16x16x32_bf16 v[46:49], v[130:133], v[198:201], v[46:49]
	v_mfma_f32_16x16x32_bf16 v[42:45], v[162:165], v[198:201], v[42:45]
	v_mfma_f32_16x16x32_bf16 v[30:33], v[130:133], v[220:223], v[30:33]
	v_mfma_f32_16x16x32_bf16 v[26:29], v[162:165], v[220:223], v[26:29]
	v_mfma_f32_16x16x32_bf16 v[14:17], v[130:133], v[228:231], v[14:17]
	v_mfma_f32_16x16x32_bf16 v[10:13], v[162:165], v[228:231], v[10:13]
	v_mfma_f32_16x16x32_bf16 v[62:65], v[158:161], v[194:197], v[62:65]
	v_mfma_f32_16x16x32_bf16 v[58:61], v[170:173], v[194:197], v[58:61]
	v_mfma_f32_16x16x32_bf16 v[46:49], v[158:161], v[216:219], v[46:49]
	v_mfma_f32_16x16x32_bf16 v[42:45], v[170:173], v[216:219], v[42:45]
	v_mfma_f32_16x16x32_bf16 v[30:33], v[158:161], v[224:227], v[30:33]
	v_mfma_f32_16x16x32_bf16 v[26:29], v[170:173], v[224:227], v[26:29]
	v_mfma_f32_16x16x32_bf16 v[14:17], v[158:161], v[232:235], v[14:17]
	v_mfma_f32_16x16x32_bf16 v[10:13], v[170:173], v[232:235], v[10:13]
	s_setprio 0
	s_setprio 1
	v_mfma_f32_16x16x32_bf16 v[54:57], v[174:177], v[190:193], v[54:57]
	v_mfma_f32_16x16x32_bf16 v[50:53], v[182:185], v[190:193], v[50:53]
	v_mfma_f32_16x16x32_bf16 v[38:41], v[174:177], v[198:201], v[38:41]
	v_mfma_f32_16x16x32_bf16 v[34:37], v[182:185], v[198:201], v[34:37]
	v_mfma_f32_16x16x32_bf16 v[22:25], v[174:177], v[220:223], v[22:25]
	v_mfma_f32_16x16x32_bf16 v[18:21], v[182:185], v[220:223], v[18:21]
	v_mfma_f32_16x16x32_bf16 v[6:9], v[174:177], v[228:231], v[6:9]
	v_mfma_f32_16x16x32_bf16 v[2:5], v[182:185], v[228:231], v[2:5]
	v_mfma_f32_16x16x32_bf16 v[54:57], v[178:181], v[194:197], v[54:57]
	v_mfma_f32_16x16x32_bf16 v[50:53], v[186:189], v[194:197], v[50:53]
	v_mfma_f32_16x16x32_bf16 v[38:41], v[178:181], v[216:219], v[38:41]
	v_mfma_f32_16x16x32_bf16 v[34:37], v[186:189], v[216:219], v[34:37]
	v_mfma_f32_16x16x32_bf16 v[22:25], v[178:181], v[224:227], v[22:25]
	v_mfma_f32_16x16x32_bf16 v[18:21], v[186:189], v[224:227], v[18:21]
	v_mfma_f32_16x16x32_bf16 v[6:9], v[178:181], v[232:235], v[6:9]
	v_mfma_f32_16x16x32_bf16 v[2:5], v[186:189], v[232:235], v[2:5]
	s_setprio 0
	s_barrier
	s_add_i32 s59, s59, 2
	s_add_u32 s57, s57, 0x100
	s_addc_u32 s58, s58, 0
	s_add_u32 s8, s8, 0x100
	s_addc_u32 s9, s9, 0
	s_cmp_gt_u32 s59, 29
	s_cbranch_scc0 .LBB0_140
	s_and_b64 vcc, exec, s[20:21]
	s_cbranch_vccz .LBB0_143
	s_barrier

.LBB0_759:
	s_or_b64 exec, exec, s[4:5]
	s_mov_b64 s[6:7], s[40:41]
	v_readlane_b32 s0, v253, 7
	s_waitcnt lgkmcnt(0)
	s_barrier
	v_mbcnt_lo_u32_b32 v0, -1, 0
	v_mbcnt_hi_u32_b32 v0, -1, v0
	v_readlane_b32 s1, v253, 8
	v_add_u32_e32 v16, s69, v0
	s_andn2_b64 vcc, exec, s[0:1]
	v_readfirstlane_b32 s0, v16
	s_cbranch_vccnz .LBB0_779
	v_lshlrev_b32_e32 v0, 4, v16
	v_add_u32_e32 v2, 0x2000, v0
	v_ashrrev_i32_e32 v3, 31, v2
	v_lshrrev_b32_e32 v3, 22, v3
	v_add_u32_e32 v3, v2, v3
	v_ashrrev_i32_e32 v10, 10, v3
	v_mul_i32_i24_e32 v3, 0x400, v10
	v_sub_u32_e32 v2, v2, v3
	v_lshrrev_b32_e32 v3, 4, v2
	v_readlane_b32 s4, v255, 6
	v_bitop3_b32 v2, v3, v2, 32 bitop3:0x6c
	s_add_u32 s16, s6, 0x13400000
	v_readlane_b32 s5, v255, 7
	v_ashrrev_i32_e32 v3, 31, v2
	s_addc_u32 s17, s7, 0
	s_lshl_b64 s[4:5], s[4:5], 23
	v_lshrrev_b32_e32 v3, 26, v3
	s_add_u32 s1, s6, s4
	v_add_u32_e32 v3, v2, v3
	v_lshlrev_b32_e32 v4, 3, v10
	s_addc_u32 s4, s7, s5
	v_ashrrev_i32_e32 v11, 6, v3
	v_and_b32_e32 v4, -16, v4
	s_add_u32 s19, s1, 0x7100000
	v_add_u32_e32 v4, v11, v4
	s_addc_u32 s28, s4, 0
	v_and_b32_e32 v5, 3, v11
	s_mov_b32 s4, 0xfffe0
	v_lshrrev_b32_e32 v6, 2, v4
	v_lshlrev_b32_e32 v7, 1, v4
	v_and_b32_e32 v3, 0xc0, v3
	v_and_or_b32 v5, v4, s4, v5
	v_and_b32_e32 v6, 4, v6
	v_and_b32_e32 v7, 24, v7
	v_sub_u32_e32 v2, v2, v3
	v_or3_b32 v5, v5, v6, v7
	v_lshlrev_b32_e32 v6, 5, v10
	v_ashrrev_i16_sdwa v2, v206, sext(v2) dst_sel:DWORD dst_unused:UNUSED_PAD src0_sel:DWORD src1_sel:BYTE_0
	v_and_b32_e32 v6, 32, v6
	v_bfe_i32 v12, v2, 0, 16
	v_add_lshl_u32 v2, v6, v12, 1
	v_lshl_add_u32 v130, v5, 12, v2
	v_lshl_add_u32 v132, v4, 12, v2
	v_bfe_i32 v2, v16, 27, 1
	v_lshrrev_b32_e32 v2, 22, v2
	v_add_u32_e32 v2, v0, v2
	v_and_b32_e32 v2, 0xfffffc00, v2
	v_sub_u32_e32 v0, v0, v2
	v_lshrrev_b32_e32 v2, 4, v0
	v_ashrrev_i32_e32 v3, 31, v16
	v_bitop3_b32 v0, v2, v0, 32 bitop3:0x6c
	v_lshrrev_b32_e32 v3, 26, v3
	v_ashrrev_i32_e32 v2, 31, v0
	v_add_u32_e32 v3, v16, v3
	v_lshrrev_b32_e32 v2, 26, v2
	v_ashrrev_i32_e32 v14, 6, v3
	v_add_u32_e32 v2, v0, v2
	v_lshlrev_b32_e32 v3, 3, v14
	v_ashrrev_i32_e32 v13, 6, v2
	v_and_b32_e32 v3, -16, v3
	v_add_u32_e32 v3, v13, v3
	v_and_b32_e32 v4, 3, v13
	v_lshrrev_b32_e32 v5, 2, v3
	v_lshlrev_b32_e32 v6, 1, v3
	v_and_b32_e32 v2, 0xc0, v2
	s_ashr_i32 s1, s0, 6
	v_and_or_b32 v4, v3, s4, v4
	v_and_b32_e32 v5, 4, v5
	v_and_b32_e32 v6, 24, v6
	v_sub_u32_e32 v0, v0, v2
	s_ashr_i32 s10, s0, 8
	s_lshl_b32 s29, s1, 10
	v_or3_b32 v4, v4, v5, v6
	v_lshlrev_b32_e32 v5, 5, v14
	v_ashrrev_i16_sdwa v0, v206, sext(v0) dst_sel:DWORD dst_unused:UNUSED_PAD src0_sel:DWORD src1_sel:BYTE_0
	v_readlane_b32 s4, v254, 20
	v_and_b32_e32 v5, 32, v5
	v_bfe_i32 v15, v0, 0, 16
	v_readlane_b32 s5, v254, 21
	s_add_u32 s26, s19, s4
	v_add_lshl_u32 v2, v5, v15, 1
	s_addc_u32 s27, s28, s5
	s_add_i32 s48, s29, 0
	v_lshl_add_u32 v0, v4, 12, v2
	s_add_i32 m0, s48, 0x10000
	v_lshl_add_u32 v134, v3, 12, v2
	global_load_lds_dwordx4 v0, s[26:27]
	s_add_i32 m0, s48, 0x12000
	s_add_u32 s4, s26, 0x80000
	global_load_lds_dwordx4 v130, s[26:27]
	s_addc_u32 s5, s27, 0
	s_add_i32 m0, s48, 0x14000
	v_mov_b32_e32 v131, v1
	global_load_lds_dwordx4 v0, s[4:5]
	s_add_i32 m0, s48, 0x16000
	v_mov_b32_e32 v135, v1
	global_load_lds_dwordx4 v130, s[4:5]
	v_readlane_b32 s4, v254, 18
	v_readlane_b32 s5, v254, 19
	s_add_u32 s80, s16, s4
	s_addc_u32 s81, s17, s5
	s_add_u32 s100, s80, s44
	s_addc_u32 s101, s81, s45
	s_add_i32 s49, s48, 0x2000
	s_mov_b32 m0, s48
	s_add_u32 s4, s80, 0x80000
	global_load_lds_dwordx4 v134, s[80:81]
	s_mov_b32 m0, s49
	s_addc_u32 s5, s81, 0
	s_add_i32 s50, s48, 0x4000
	global_load_lds_dwordx4 v132, s[80:81]
	s_mov_b32 m0, s50
	s_add_i32 s51, s48, 0x6000
	global_load_lds_dwordx4 v134, s[4:5]
	s_mov_b32 m0, s51
	v_mov_b32_e32 v133, v1
	global_load_lds_dwordx4 v132, s[4:5]
	s_cmp_eq_u32 s10, 1
	v_lshl_add_u64 v[8:9], s[26:27], 0, v[0:1]
	v_lshl_add_u64 v[6:7], s[26:27], 0, v[130:131]
	v_lshl_add_u64 v[2:3], s[80:81], 0, v[134:135]
	s_cselect_b64 s[4:5], -1, 0
	s_cmp_lg_u32 s10, 1
	v_lshl_add_u64 v[4:5], s[80:81], 0, v[132:133]
	s_cbranch_scc1 .LBB0_762
	s_barrier

.LBB0_772:
	s_add_u32 s60, s26, 0xfff80080
	s_addc_u32 s61, s27, -1
	s_add_i32 s62, 0, 0x10000
	s_cmp_eq_u32 s59, 28
	s_cselect_b32 s87, s0, s61
	s_cselect_b32 s86, s1, s60
	v_add_u32_e32 v140, s62, v143
	s_cselect_b32 s81, s13, s58
	s_cselect_b32 s80, s15, s57
	s_add_i32 s63, 0, 0x14000
	ds_read_b128 v[156:159], v140
	ds_read_b128 v[160:163], v140 offset:1024
	ds_read_b128 v[164:167], v140 offset:2048
	ds_read_b128 v[168:171], v140 offset:3072
	v_add_u32_e32 v140, s63, v143
	ds_read_b128 v[172:175], v140
	ds_read_b128 v[176:179], v140 offset:1024
	ds_read_b128 v[180:183], v140 offset:2048
	ds_read_b128 v[184:187], v140 offset:3072
	s_mov_b32 m0, s52
	s_nop 0
	global_load_lds_dwordx4 v134, s[100:101]
	s_mov_b32 m0, s53
	s_nop 0
	global_load_lds_dwordx4 v132, s[100:101]
	s_add_i32 m0, s48, 0xc000
	ds_read_b128 v[188:191], v145
	ds_read_b128 v[192:195], v145 offset:1024
	ds_read_b128 v[196:199], v145 offset:2048
	ds_read_b128 v[200:203], v145 offset:3072
	ds_read_b128 v[218:221], v145 offset:4096
	ds_read_b128 v[222:225], v145 offset:5120
	ds_read_b128 v[226:229], v145 offset:6144
	ds_read_b128 v[230:233], v145 offset:7168
	global_load_lds_dwordx4 v138, s[26:27]
	s_add_i32 m0, s48, 0xe000
	s_nop 0
	global_load_lds_dwordx4 v136, s[26:27]
	s_waitcnt vmcnt(8)
	s_waitcnt lgkmcnt(0)
	s_barrier
	s_setprio 1
	s_waitcnt lgkmcnt(0)
	v_mfma_f32_16x16x32_bf16 v[126:129], v[156:159], v[188:191], v[126:129]
	v_mfma_f32_16x16x32_bf16 v[122:125], v[164:167], v[188:191], v[122:125]
	v_mfma_f32_16x16x32_bf16 v[118:121], v[156:159], v[196:199], v[118:121]
	v_mfma_f32_16x16x32_bf16 v[110:113], v[164:167], v[196:199], v[110:113]
	v_mfma_f32_16x16x32_bf16 v[102:105], v[156:159], v[218:221], v[102:105]
	v_mfma_f32_16x16x32_bf16 v[94:97], v[164:167], v[218:221], v[94:97]
	v_mfma_f32_16x16x32_bf16 v[86:89], v[156:159], v[226:229], v[86:89]
	v_mfma_f32_16x16x32_bf16 v[78:81], v[164:167], v[226:229], v[78:81]
	v_mfma_f32_16x16x32_bf16 v[126:129], v[160:163], v[192:195], v[126:129]
	v_mfma_f32_16x16x32_bf16 v[122:125], v[168:171], v[192:195], v[122:125]
	v_mfma_f32_16x16x32_bf16 v[118:121], v[160:163], v[200:203], v[118:121]
	v_mfma_f32_16x16x32_bf16 v[110:113], v[168:171], v[200:203], v[110:113]
	v_mfma_f32_16x16x32_bf16 v[102:105], v[160:163], v[222:225], v[102:105]
	v_mfma_f32_16x16x32_bf16 v[94:97], v[168:171], v[222:225], v[94:97]
	v_mfma_f32_16x16x32_bf16 v[86:89], v[160:163], v[230:233], v[86:89]
	v_mfma_f32_16x16x32_bf16 v[78:81], v[168:171], v[230:233], v[78:81]
	s_setprio 0
	s_setprio 1
	v_mfma_f32_16x16x32_bf16 v[114:117], v[172:175], v[188:191], v[114:117]
	v_mfma_f32_16x16x32_bf16 v[106:109], v[180:183], v[188:191], v[106:109]
	v_mfma_f32_16x16x32_bf16 v[98:101], v[172:175], v[196:199], v[98:101]
	v_mfma_f32_16x16x32_bf16 v[90:93], v[180:183], v[196:199], v[90:93]
	v_mfma_f32_16x16x32_bf16 v[82:85], v[172:175], v[218:221], v[82:85]
	v_mfma_f32_16x16x32_bf16 v[74:77], v[180:183], v[218:221], v[74:77]
	v_mfma_f32_16x16x32_bf16 v[70:73], v[172:175], v[226:229], v[70:73]
	v_mfma_f32_16x16x32_bf16 v[66:69], v[180:183], v[226:229], v[66:69]
	v_mfma_f32_16x16x32_bf16 v[114:117], v[176:179], v[192:195], v[114:117]
	v_mfma_f32_16x16x32_bf16 v[106:109], v[184:187], v[192:195], v[106:109]
	v_mfma_f32_16x16x32_bf16 v[98:101], v[176:179], v[200:203], v[98:101]
	v_mfma_f32_16x16x32_bf16 v[90:93], v[184:187], v[200:203], v[90:93]
	v_mfma_f32_16x16x32_bf16 v[82:85], v[176:179], v[222:225], v[82:85]
	v_mfma_f32_16x16x32_bf16 v[74:77], v[184:187], v[222:225], v[74:77]
	v_mfma_f32_16x16x32_bf16 v[70:73], v[176:179], v[230:233], v[70:73]
	v_mfma_f32_16x16x32_bf16 v[66:69], v[184:187], v[230:233], v[66:69]
	s_setprio 0
	s_barrier
	s_add_i32 s60, s62, s29
	s_add_u32 s88, s80, s44
	s_addc_u32 s89, s81, s45
	s_mov_b32 m0, s60
	ds_read_b128 v[188:191], v145 offset:16384
	ds_read_b128 v[192:195], v145 offset:17408
	ds_read_b128 v[196:199], v145 offset:18432
	ds_read_b128 v[200:203], v145 offset:19456
	ds_read_b128 v[218:221], v145 offset:20480
	ds_read_b128 v[222:225], v145 offset:21504
	ds_read_b128 v[226:229], v145 offset:22528
	ds_read_b128 v[230:233], v145 offset:23552
	global_load_lds_dwordx4 v0, s[80:81]
	s_add_i32 m0, s60, 0x2000
	s_add_u32 s60, s80, 0x80000
	s_addc_u32 s61, s81, 0
	s_add_i32 s62, s63, s29
	global_load_lds_dwordx4 v130, s[80:81]
	s_mov_b32 m0, s62
	s_add_u32 s100, s86, s44
	s_addc_u32 s101, s87, s45
	global_load_lds_dwordx4 v0, s[60:61]
	s_add_i32 m0, s62, 0x2000
	s_nop 0
	global_load_lds_dwordx4 v130, s[60:61]
	s_waitcnt vmcnt(6)
	s_waitcnt lgkmcnt(0)
	s_barrier
	s_setprio 1
	s_waitcnt lgkmcnt(0)
	v_mfma_f32_16x16x32_bf16 v[62:65], v[156:159], v[188:191], v[62:65]
	v_mfma_f32_16x16x32_bf16 v[58:61], v[164:167], v[188:191], v[58:61]
	v_mfma_f32_16x16x32_bf16 v[54:57], v[156:159], v[196:199], v[54:57]
	v_mfma_f32_16x16x32_bf16 v[46:49], v[164:167], v[196:199], v[46:49]
	v_mfma_f32_16x16x32_bf16 v[38:41], v[156:159], v[218:221], v[38:41]
	v_mfma_f32_16x16x32_bf16 v[30:33], v[164:167], v[218:221], v[30:33]
	v_mfma_f32_16x16x32_bf16 v[22:25], v[156:159], v[226:229], v[22:25]
	v_mfma_f32_16x16x32_bf16 v[14:17], v[164:167], v[226:229], v[14:17]
	v_mfma_f32_16x16x32_bf16 v[62:65], v[160:163], v[192:195], v[62:65]
	v_mfma_f32_16x16x32_bf16 v[58:61], v[168:171], v[192:195], v[58:61]
	v_mfma_f32_16x16x32_bf16 v[54:57], v[160:163], v[200:203], v[54:57]
	v_mfma_f32_16x16x32_bf16 v[46:49], v[168:171], v[200:203], v[46:49]
	v_mfma_f32_16x16x32_bf16 v[38:41], v[160:163], v[222:225], v[38:41]
	v_mfma_f32_16x16x32_bf16 v[30:33], v[168:171], v[222:225], v[30:33]
	v_mfma_f32_16x16x32_bf16 v[22:25], v[160:163], v[230:233], v[22:25]
	v_mfma_f32_16x16x32_bf16 v[14:17], v[168:171], v[230:233], v[14:17]
	s_setprio 0
	s_setprio 1
	v_mfma_f32_16x16x32_bf16 v[50:53], v[172:175], v[188:191], v[50:53]
	v_mfma_f32_16x16x32_bf16 v[42:45], v[180:183], v[188:191], v[42:45]
	v_mfma_f32_16x16x32_bf16 v[34:37], v[172:175], v[196:199], v[34:37]
	v_mfma_f32_16x16x32_bf16 v[26:29], v[180:183], v[196:199], v[26:29]
	v_mfma_f32_16x16x32_bf16 v[18:21], v[172:175], v[218:221], v[18:21]
	v_mfma_f32_16x16x32_bf16 v[10:13], v[180:183], v[218:221], v[10:13]
	v_mfma_f32_16x16x32_bf16 v[6:9], v[172:175], v[226:229], v[6:9]
	v_mfma_f32_16x16x32_bf16 v[2:5], v[180:183], v[226:229], v[2:5]
	v_mfma_f32_16x16x32_bf16 v[50:53], v[176:179], v[192:195], v[50:53]
	v_mfma_f32_16x16x32_bf16 v[42:45], v[184:187], v[192:195], v[42:45]
	v_mfma_f32_16x16x32_bf16 v[34:37], v[176:179], v[200:203], v[34:37]
	v_mfma_f32_16x16x32_bf16 v[26:29], v[184:187], v[200:203], v[26:29]
	v_mfma_f32_16x16x32_bf16 v[18:21], v[176:179], v[222:225], v[18:21]
	v_mfma_f32_16x16x32_bf16 v[10:13], v[184:187], v[222:225], v[10:13]
	v_mfma_f32_16x16x32_bf16 v[6:9], v[176:179], v[230:233], v[6:9]
	v_mfma_f32_16x16x32_bf16 v[2:5], v[184:187], v[230:233], v[2:5]
	s_setprio 0
	s_barrier
	s_add_i32 s62, 0, 0x18000
	s_add_i32 s63, 0, 0x1c000
	v_add_u32_e32 v168, s62, v143
	v_add_u32_e32 v184, s63, v143
	ds_read_b128 v[156:159], v168
	ds_read_b128 v[160:163], v168 offset:1024
	ds_read_b128 v[164:167], v168 offset:2048
	ds_read_b128 v[168:171], v168 offset:3072
	ds_read_b128 v[172:175], v184
	ds_read_b128 v[176:179], v184 offset:1024
	ds_read_b128 v[180:183], v184 offset:2048
	ds_read_b128 v[184:187], v184 offset:3072
	s_mov_b32 m0, s48
	s_nop 0
	global_load_lds_dwordx4 v134, s[86:87]
	s_mov_b32 m0, s49
	s_nop 0
	global_load_lds_dwordx4 v132, s[86:87]
	s_add_u32 s60, s86, 0x80000
	s_addc_u32 s61, s87, 0
	s_mov_b32 m0, s50
	ds_read_b128 v[188:191], v145 offset:32768
	ds_read_b128 v[192:195], v145 offset:33792
	ds_read_b128 v[196:199], v145 offset:34816
	ds_read_b128 v[200:203], v145 offset:35840
	ds_read_b128 v[218:221], v145 offset:36864
	ds_read_b128 v[222:225], v145 offset:37888
	ds_read_b128 v[226:229], v145 offset:38912
	ds_read_b128 v[230:233], v145 offset:39936
	global_load_lds_dwordx4 v134, s[60:61]
	s_mov_b32 m0, s51
	s_nop 0
	global_load_lds_dwordx4 v132, s[60:61]
	s_waitcnt vmcnt(8)
	s_waitcnt lgkmcnt(0)
	s_barrier
	s_setprio 1
	s_waitcnt lgkmcnt(0)
	v_mfma_f32_16x16x32_bf16 v[126:129], v[156:159], v[188:191], v[126:129]
	v_mfma_f32_16x16x32_bf16 v[122:125], v[164:167], v[188:191], v[122:125]
	v_mfma_f32_16x16x32_bf16 v[118:121], v[156:159], v[196:199], v[118:121]
	v_mfma_f32_16x16x32_bf16 v[110:113], v[164:167], v[196:199], v[110:113]
	v_mfma_f32_16x16x32_bf16 v[102:105], v[156:159], v[218:221], v[102:105]
	v_mfma_f32_16x16x32_bf16 v[94:97], v[164:167], v[218:221], v[94:97]
	v_mfma_f32_16x16x32_bf16 v[86:89], v[156:159], v[226:229], v[86:89]
	v_mfma_f32_16x16x32_bf16 v[78:81], v[164:167], v[226:229], v[78:81]
	v_mfma_f32_16x16x32_bf16 v[126:129], v[160:163], v[192:195], v[126:129]
	v_mfma_f32_16x16x32_bf16 v[122:125], v[168:171], v[192:195], v[122:125]
	v_mfma_f32_16x16x32_bf16 v[118:121], v[160:163], v[200:203], v[118:121]
	v_mfma_f32_16x16x32_bf16 v[110:113], v[168:171], v[200:203], v[110:113]
	v_mfma_f32_16x16x32_bf16 v[102:105], v[160:163], v[222:225], v[102:105]
	v_mfma_f32_16x16x32_bf16 v[94:97], v[168:171], v[222:225], v[94:97]
	v_mfma_f32_16x16x32_bf16 v[86:89], v[160:163], v[230:233], v[86:89]
	v_mfma_f32_16x16x32_bf16 v[78:81], v[168:171], v[230:233], v[78:81]
	s_setprio 0
	s_setprio 1
	v_mfma_f32_16x16x32_bf16 v[114:117], v[172:175], v[188:191], v[114:117]
	v_mfma_f32_16x16x32_bf16 v[106:109], v[180:183], v[188:191], v[106:109]
	v_mfma_f32_16x16x32_bf16 v[98:101], v[172:175], v[196:199], v[98:101]
	v_mfma_f32_16x16x32_bf16 v[90:93], v[180:183], v[196:199], v[90:93]
	v_mfma_f32_16x16x32_bf16 v[82:85], v[172:175], v[218:221], v[82:85]
	v_mfma_f32_16x16x32_bf16 v[74:77], v[180:183], v[218:221], v[74:77]
	v_mfma_f32_16x16x32_bf16 v[70:73], v[172:175], v[226:229], v[70:73]
	v_mfma_f32_16x16x32_bf16 v[66:69], v[180:183], v[226:229], v[66:69]
	v_mfma_f32_16x16x32_bf16 v[114:117], v[176:179], v[192:195], v[114:117]
	v_mfma_f32_16x16x32_bf16 v[106:109], v[184:187], v[192:195], v[106:109]
	v_mfma_f32_16x16x32_bf16 v[98:101], v[176:179], v[200:203], v[98:101]
	v_mfma_f32_16x16x32_bf16 v[90:93], v[184:187], v[200:203], v[90:93]
	v_mfma_f32_16x16x32_bf16 v[82:85], v[176:179], v[222:225], v[82:85]
	v_mfma_f32_16x16x32_bf16 v[74:77], v[184:187], v[222:225], v[74:77]
	v_mfma_f32_16x16x32_bf16 v[70:73], v[176:179], v[230:233], v[70:73]
	v_mfma_f32_16x16x32_bf16 v[66:69], v[184:187], v[230:233], v[66:69]
	s_setprio 0
	s_barrier
	s_add_i32 s60, s62, s29
	s_mov_b32 m0, s60
	ds_read_b128 v[188:191], v145 offset:49152
	ds_read_b128 v[192:195], v145 offset:50176
	ds_read_b128 v[196:199], v145 offset:51200
	ds_read_b128 v[200:203], v145 offset:52224
	ds_read_b128 v[218:221], v145 offset:53248
	ds_read_b128 v[222:225], v145 offset:54272
	ds_read_b128 v[226:229], v145 offset:55296
	ds_read_b128 v[230:233], v145 offset:56320
	global_load_lds_dwordx4 v0, s[88:89]
	s_add_i32 m0, s60, 0x2000
	s_add_u32 s60, s80, 0x80080
	s_addc_u32 s61, s81, 0
	s_add_i32 s62, s63, s29
	global_load_lds_dwordx4 v130, s[88:89]
	s_mov_b32 m0, s62
	s_nop 0
	global_load_lds_dwordx4 v0, s[60:61]
	s_add_i32 m0, s62, 0x2000
	s_nop 0
	global_load_lds_dwordx4 v130, s[60:61]
	s_waitcnt vmcnt(6)
	s_waitcnt lgkmcnt(0)
	s_barrier
	s_setprio 1
	s_waitcnt lgkmcnt(0)
	v_mfma_f32_16x16x32_bf16 v[62:65], v[156:159], v[188:191], v[62:65]
	v_mfma_f32_16x16x32_bf16 v[58:61], v[164:167], v[188:191], v[58:61]
	v_mfma_f32_16x16x32_bf16 v[54:57], v[156:159], v[196:199], v[54:57]
	v_mfma_f32_16x16x32_bf16 v[46:49], v[164:167], v[196:199], v[46:49]
	v_mfma_f32_16x16x32_bf16 v[38:41], v[156:159], v[218:221], v[38:41]
	v_mfma_f32_16x16x32_bf16 v[30:33], v[164:167], v[218:221], v[30:33]
	v_mfma_f32_16x16x32_bf16 v[22:25], v[156:159], v[226:229], v[22:25]
	v_mfma_f32_16x16x32_bf16 v[14:17], v[164:167], v[226:229], v[14:17]
	v_mfma_f32_16x16x32_bf16 v[62:65], v[160:163], v[192:195], v[62:65]
	v_mfma_f32_16x16x32_bf16 v[58:61], v[168:171], v[192:195], v[58:61]
	v_mfma_f32_16x16x32_bf16 v[54:57], v[160:163], v[200:203], v[54:57]
	v_mfma_f32_16x16x32_bf16 v[46:49], v[168:171], v[200:203], v[46:49]
	v_mfma_f32_16x16x32_bf16 v[38:41], v[160:163], v[222:225], v[38:41]
	v_mfma_f32_16x16x32_bf16 v[30:33], v[168:171], v[222:225], v[30:33]
	v_mfma_f32_16x16x32_bf16 v[22:25], v[160:163], v[230:233], v[22:25]
	v_mfma_f32_16x16x32_bf16 v[14:17], v[168:171], v[230:233], v[14:17]
	s_setprio 0
	s_setprio 1
	v_mfma_f32_16x16x32_bf16 v[50:53], v[172:175], v[188:191], v[50:53]
	v_mfma_f32_16x16x32_bf16 v[42:45], v[180:183], v[188:191], v[42:45]
	v_mfma_f32_16x16x32_bf16 v[34:37], v[172:175], v[196:199], v[34:37]
	v_mfma_f32_16x16x32_bf16 v[26:29], v[180:183], v[196:199], v[26:29]
	v_mfma_f32_16x16x32_bf16 v[18:21], v[172:175], v[218:221], v[18:21]
	v_mfma_f32_16x16x32_bf16 v[10:13], v[180:183], v[218:221], v[10:13]
	v_mfma_f32_16x16x32_bf16 v[6:9], v[172:175], v[226:229], v[6:9]
	v_mfma_f32_16x16x32_bf16 v[2:5], v[180:183], v[226:229], v[2:5]
	v_mfma_f32_16x16x32_bf16 v[50:53], v[176:179], v[192:195], v[50:53]
	v_mfma_f32_16x16x32_bf16 v[42:45], v[184:187], v[192:195], v[42:45]
	v_mfma_f32_16x16x32_bf16 v[34:37], v[176:179], v[200:203], v[34:37]
	v_mfma_f32_16x16x32_bf16 v[26:29], v[184:187], v[200:203], v[26:29]
	v_mfma_f32_16x16x32_bf16 v[18:21], v[176:179], v[222:225], v[18:21]
	v_mfma_f32_16x16x32_bf16 v[10:13], v[184:187], v[222:225], v[10:13]
	v_mfma_f32_16x16x32_bf16 v[6:9], v[176:179], v[230:233], v[6:9]
	v_mfma_f32_16x16x32_bf16 v[2:5], v[184:187], v[230:233], v[2:5]
	s_setprio 0
	s_barrier
	s_add_i32 s59, s59, 2
	s_add_u32 s57, s57, 0x100
	s_addc_u32 s58, s58, 0
	s_add_u32 s26, s26, 0x100
	s_addc_u32 s27, s27, 0
	s_cmp_gt_u32 s59, 29
	s_cbranch_scc0 .LBB0_772
	s_and_b64 vcc, exec, s[10:11]
	v_readlane_b32 s58, v254, 35
	v_readlane_b32 s59, v254, 36
	s_cbranch_vccz .LBB0_775
	s_barrier
